# S4 selection: wave-wide min/max of the score row by DPP row reductions and v_permlane16/32_swap instead of twelve ds_bpermute round trips
# baseline (speedup 1.0000x reference)
; __device__ __forceinline__ void select_threshold_wg(const LAS float* sc, int nv, int ksel, LAS unsigned* scr, int tid, float& tau_o, int& idx_o) {
;     ...
;     if (nv >= MK_THREADS && ksel <= MK_THREADS) lo = hi;
;     lo = -wmax(-lo); hi = wmax(hi); if (lane == 0) { part[wave] = lo; part[8 + wave] = hi; }
;     __syncthreads();
; #pragma unroll
;     for (int w = 0; w < 8; ++w) { lo = fminf(lo, part[w]); hi = fmaxf(hi, part[8 + w]); }
.LBB0_1115:
	s_or_b64 exec, exec, s[2:3]
	v_xor_b32_e32 v22, 0x80000000, v23
	s_ashr_i32 s3, s59, 6
	s_nop 0
	v_max_f32_dpp v22, v22, v22 quad_perm:[1,0,3,2] row_mask:0xf bank_mask:0xf
	v_max_f32_dpp v23, v23, v23 quad_perm:[1,0,3,2] row_mask:0xf bank_mask:0xf
	s_nop 0
	v_max_f32_dpp v22, v22, v22 quad_perm:[2,3,0,1] row_mask:0xf bank_mask:0xf
	v_max_f32_dpp v23, v23, v23 quad_perm:[2,3,0,1] row_mask:0xf bank_mask:0xf
	s_nop 0
	v_max_f32_dpp v22, v22, v22 row_half_mirror row_mask:0xf bank_mask:0xf
	v_max_f32_dpp v23, v23, v23 row_half_mirror row_mask:0xf bank_mask:0xf
	s_nop 0
	v_max_f32_dpp v22, v22, v22 row_mirror row_mask:0xf bank_mask:0xf
	v_max_f32_dpp v23, v23, v23 row_mirror row_mask:0xf bank_mask:0xf
	s_nop 0
	v_mov_b32_e32 v24, v22
	v_mov_b32_e32 v25, v23
	s_nop 1
	v_permlane16_swap_b32_e32 v22, v24
	v_permlane16_swap_b32_e32 v23, v25
	v_max_f32_e32 v22, v22, v24
	v_max_f32_e32 v23, v23, v25
	v_mov_b32_e32 v24, v22
	v_mov_b32_e32 v25, v23
	s_nop 1
	v_permlane32_swap_b32_e32 v22, v24
	v_permlane32_swap_b32_e32 v23, v25
	v_max_f32_e32 v22, v22, v24
	v_max_f32_e32 v23, v23, v25
	s_and_saveexec_b64 s[0:1], s[14:15]
	s_cbranch_execz .LBB0_1117
	s_lshl_b32 s2, s3, 2
	s_add_i32 s2, s2, 0
	v_mov_b32_e32 v25, s2
	v_xor_b32_e32 v24, 0x80000000, v22
	v_add_u32_e32 v25, 0xb000, v25
	ds_write2_b32 v25, v24, v23 offset0:216 offset1:224
